# P7 loop-end waits relaxed to vmcnt 5/4/3/2 so the per-chunk E-store acks are not waited on (loads are older in the queue)
# baseline (speedup 1.0000x reference)
; template <int DIR>
; __device__ __forceinline__ void s5_local_dir(const bf16_t* UZ, unsigned char* ws, int gw, int NGW, int lane) {
;     ...
;     for (int c = c0; c < c1; ++c) {
;         bf16x4 Uf[4];
; #pragma unroll
;         for (int m = 0; m < 4; ++m) Uf[m] = Un[m];
;         if (c + 1 < c1) load_uf(Un, UZ, chunk_rowbase(b, DIR, c + 1), g, lane);
;         float* e = ebase + (size_t)c * 128;
; #pragma unroll
;         for (int t = 0; t < 4; ++t) {
;             f32x4 cr = {0.f, 0.f, 0.f, 0.f}, ci = {0.f, 0.f, 0.f, 0.f};
; #pragma unroll
;             for (int m = 0; m < 4; ++m) {
;                 cr = __builtin_amdgcn_mfma_f32_16x16x16bf16_1k(Uf[m], Bre[m][t], cr, 0, 0, 0);
;                 ci = __builtin_amdgcn_mfma_f32_16x16x16bf16_1k(Uf[m], Bim[m][t], ci, 0, 0, 0);
;             }
;             f32x2 s2 = {DIR ? cr[3] : cr[0], DIR ? ci[3] : ci[0]};
; #pragma unroll
;             for (int ii = 1; ii < 4; ++ii) { const int i = DIR ? 3 - ii : ii;
;                 s2 = cmac(s2, (f32x2){a1r[t], a1r[t]}, (f32x2){-a1i[t], a1i[t]}, (f32x2){cr[i], ci[i]}); }
;             s2 = cmac(s2, (f32x2){wr_[t], wr_[t]}, (f32x2){-wi_[t], wi_[t]}, (f32x2){0.f, 0.f});
;             float sr = s2.x, si = s2.y;
;             sr += __shfl_xor(sr, 16); si += __shfl_xor(si, 16); sr += __shfl_xor(sr, 32); si += __shfl_xor(si, 32);
;             if (fq == 0) { e[16 * t + fr] = Rr[t]; e[64 + 16 * t + fr] = Ri[t]; }
;             const float nr = fmaf(a64r[t], Rr[t], fmaf(-a64i[t], Ri[t], sr)), ni = fmaf(a64r[t], Ri[t], fmaf(a64i[t], Rr[t], si)); Rr[t] = nr; Ri[t] = ni;
;         }
;     }
.LBB0_652:
	global_store_dword v[116:117], v240, off offset:-256
	global_store_dword v[116:117], v241, off
	s_waitcnt vmcnt(9)
	v_mfma_f32_16x16x32_bf16 v[140:143], v[108:111], v[26:29], 0
	v_mfma_f32_16x16x32_bf16 v[144:147], v[108:111], v[34:37], 0
	v_mfma_f32_16x16x32_bf16 v[196:199], v[108:111], v[48:51], 0
	v_mfma_f32_16x16x32_bf16 v[200:203], v[108:111], v[56:59], 0
	v_mfma_f32_16x16x32_bf16 v[208:211], v[108:111], v[70:73], 0
	v_mfma_f32_16x16x32_bf16 v[212:215], v[108:111], v[78:81], 0
	v_mfma_f32_16x16x32_bf16 v[228:231], v[108:111], v[92:95], 0
	v_mfma_f32_16x16x32_bf16 v[184:187], v[108:111], v[100:103], 0
	v_mfma_f32_16x16x32_bf16 v[140:143], v[112:115], v[30:33], v[140:143]
	v_mfma_f32_16x16x32_bf16 v[144:147], v[112:115], v[38:41], v[144:147]
	v_mfma_f32_16x16x32_bf16 v[196:199], v[112:115], v[52:55], v[196:199]
	v_mfma_f32_16x16x32_bf16 v[200:203], v[112:115], v[60:63], v[200:203]
	v_mfma_f32_16x16x32_bf16 v[208:211], v[112:115], v[74:77], v[208:211]
	v_mfma_f32_16x16x32_bf16 v[212:215], v[112:115], v[82:85], v[212:215]
	v_mfma_f32_16x16x32_bf16 v[228:231], v[112:115], v[96:99], v[228:231]
	v_mfma_f32_16x16x32_bf16 v[184:187], v[112:115], v[104:107], v[184:187]
	s_nop 6
	v_mov_b32_e32 v148, v143
	v_mov_b32_e32 v204, v199
	v_mov_b32_e32 v216, v211
	v_mov_b32_e32 v190, v231
	v_mov_b32_e32 v149, v147
	v_mov_b32_e32 v205, v203
	v_mov_b32_e32 v217, v215
	v_mov_b32_e32 v191, v187
	v_mov_b32_e32 v150, v142
	v_mov_b32_e32 v206, v198
	v_mov_b32_e32 v218, v210
	v_mov_b32_e32 v188, v230
	v_mov_b32_e32 v151, v146
	v_mov_b32_e32 v207, v202
	v_mov_b32_e32 v219, v214
	v_mov_b32_e32 v189, v186
	v_pk_fma_f32 v[148:149], v[20:21], v[148:149], v[150:151]
	v_pk_fma_f32 v[204:205], v[42:43], v[204:205], v[206:207]
	v_pk_fma_f32 v[216:217], v[64:65], v[216:217], v[218:219]
	v_pk_fma_f32 v[188:189], v[86:87], v[190:191], v[188:189]
	v_mov_b32_e32 v142, v147
	v_mov_b32_e32 v198, v203
	v_mov_b32_e32 v210, v215
	v_mov_b32_e32 v230, v187
	v_pk_fma_f32 v[142:143], v[0:1], v[142:143], v[148:149]
	v_pk_fma_f32 v[198:199], v[4:5], v[198:199], v[204:205]
	v_pk_fma_f32 v[210:211], v[8:9], v[210:211], v[216:217]
	v_pk_fma_f32 v[186:187], v[12:13], v[230:231], v[188:189]
	v_mov_b32_e32 v146, v141
	v_mov_b32_e32 v202, v197
	v_mov_b32_e32 v214, v209
	v_mov_b32_e32 v188, v229
	v_mov_b32_e32 v147, v145
	v_mov_b32_e32 v203, v201
	v_mov_b32_e32 v215, v213
	v_mov_b32_e32 v189, v185
	v_pk_fma_f32 v[146:147], v[20:21], v[142:143], v[146:147]
	v_pk_fma_f32 v[202:203], v[42:43], v[198:199], v[202:203]
	v_pk_fma_f32 v[214:215], v[64:65], v[210:211], v[214:215]
	v_pk_fma_f32 v[188:189], v[86:87], v[186:187], v[188:189]
	v_mov_b32_e32 v141, v144
	v_mov_b32_e32 v197, v200
	v_mov_b32_e32 v209, v212
	v_mov_b32_e32 v229, v184
	v_pk_fma_f32 v[142:143], v[0:1], v[142:143], v[146:147] op_sel:[0,1,0] op_sel_hi:[1,0,1]
	v_pk_fma_f32 v[198:199], v[4:5], v[198:199], v[202:203] op_sel:[0,1,0] op_sel_hi:[1,0,1]
	v_pk_fma_f32 v[210:211], v[8:9], v[210:211], v[214:215] op_sel:[0,1,0] op_sel_hi:[1,0,1]
	v_pk_fma_f32 v[186:187], v[12:13], v[186:187], v[188:189] op_sel:[0,1,0] op_sel_hi:[1,0,1]
	s_nop 0
	s_nop 0
	s_nop 0
	s_nop 0
	v_pk_fma_f32 v[140:141], v[20:21], v[142:143], v[140:141]
	v_pk_fma_f32 v[196:197], v[42:43], v[198:199], v[196:197]
	v_pk_fma_f32 v[208:209], v[64:65], v[210:211], v[208:209]
	v_pk_fma_f32 v[184:185], v[86:87], v[186:187], v[228:229]
	s_nop 0
	s_nop 0
	s_nop 0
	s_nop 0
	v_pk_fma_f32 v[140:141], v[0:1], v[142:143], v[140:141] op_sel:[0,1,0] op_sel_hi:[1,0,1]
	v_pk_fma_f32 v[196:197], v[4:5], v[198:199], v[196:197] op_sel:[0,1,0] op_sel_hi:[1,0,1]
	v_pk_fma_f32 v[208:209], v[8:9], v[210:211], v[208:209] op_sel:[0,1,0] op_sel_hi:[1,0,1]
	v_pk_fma_f32 v[184:185], v[12:13], v[186:187], v[184:185] op_sel:[0,1,0] op_sel_hi:[1,0,1]
	s_nop 0
	s_nop 0
	s_nop 0
	s_nop 0
	v_pk_fma_f32 v[142:143], v[22:23], v[140:141], 0 op_sel_hi:[1,1,0]
	v_pk_fma_f32 v[198:199], v[44:45], v[196:197], 0 op_sel_hi:[1,1,0]
	v_pk_fma_f32 v[210:211], v[66:67], v[208:209], 0 op_sel_hi:[1,1,0]
	v_pk_fma_f32 v[186:187], v[88:89], v[184:185], 0 op_sel_hi:[1,1,0]
	s_nop 0
	s_nop 0
	s_nop 0
	s_nop 0
	v_pk_fma_f32 v[140:141], v[24:25], v[140:141], v[142:143] op_sel:[0,1,0] op_sel_hi:[1,0,1]
	v_pk_fma_f32 v[196:197], v[46:47], v[196:197], v[198:199] op_sel:[0,1,0] op_sel_hi:[1,0,1]
	v_pk_fma_f32 v[208:209], v[68:69], v[208:209], v[210:211] op_sel:[0,1,0] op_sel_hi:[1,0,1]
	v_pk_fma_f32 v[184:185], v[90:91], v[184:185], v[186:187] op_sel:[0,1,0] op_sel_hi:[1,0,1]
	s_nop 1
	v_permlane32_swap_b32_e32 v140, v208
	v_permlane32_swap_b32_e32 v141, v209
	v_permlane32_swap_b32_e32 v196, v184
	v_permlane32_swap_b32_e32 v197, v185
	v_add_f32_e32 v140, v140, v208
	v_add_f32_e32 v196, v196, v184
	v_add_f32_e32 v141, v141, v209
	v_add_f32_e32 v197, v197, v185
	s_nop 0
	v_permlane16_swap_b32_e32 v140, v196
	v_permlane16_swap_b32_e32 v141, v197
	v_add_f32_e32 v140, v140, v196
	v_add_f32_e32 v141, v141, v197
	v_fma_f32 v244, -v243, v241, v140
	v_fma_f32 v245, v243, v240, v141
	v_fma_f32 v240, v242, v240, v244
	v_fma_f32 v241, v242, v241, v245
	v_lshl_add_u64 v[116:117], v[116:117], 0, s[2:3]
	v_subrev_u32_e32 v16, 64, v16
	s_and_b64 vcc, exec, s[36:37]
	s_cbranch_vccnz .LBB0_684
	s_mov_b32 s38, s49
	s_waitcnt vmcnt(5)
	v_mov_b32_e32 v110, v118
	v_mov_b32_e32 v111, v119
	s_waitcnt vmcnt(4)
	v_mov_b32_e32 v112, v120
	v_mov_b32_e32 v113, v121
	s_waitcnt vmcnt(3)
	v_mov_b32_e32 v114, v122
	v_mov_b32_e32 v115, v123
	s_waitcnt vmcnt(2)
	v_mov_b32_e32 v108, v124
	v_mov_b32_e32 v109, v125
	s_branch .LBB0_649

; template <int DIR>
; __device__ __forceinline__ void s5_local_dir(const bf16_t* UZ, unsigned char* ws, int gw, int NGW, int lane) {
;     ...
;     for (int c = c0; c < c1; ++c) {
;         bf16x4 Uf[4];
; #pragma unroll
;         for (int m = 0; m < 4; ++m) Uf[m] = Un[m];
;         if (c + 1 < c1) load_uf(Un, UZ, chunk_rowbase(b, DIR, c + 1), g, lane);
;         float* e = ebase + (size_t)c * 128;
; #pragma unroll
;         for (int t = 0; t < 4; ++t) {
;             f32x4 cr = {0.f, 0.f, 0.f, 0.f}, ci = {0.f, 0.f, 0.f, 0.f};
; #pragma unroll
;             for (int m = 0; m < 4; ++m) {
;                 cr = __builtin_amdgcn_mfma_f32_16x16x16bf16_1k(Uf[m], Bre[m][t], cr, 0, 0, 0);
;                 ci = __builtin_amdgcn_mfma_f32_16x16x16bf16_1k(Uf[m], Bim[m][t], ci, 0, 0, 0);
;             }
;             f32x2 s2 = {DIR ? cr[3] : cr[0], DIR ? ci[3] : ci[0]};
; #pragma unroll
;             for (int ii = 1; ii < 4; ++ii) { const int i = DIR ? 3 - ii : ii;
;                 s2 = cmac(s2, (f32x2){a1r[t], a1r[t]}, (f32x2){-a1i[t], a1i[t]}, (f32x2){cr[i], ci[i]}); }
;             s2 = cmac(s2, (f32x2){wr_[t], wr_[t]}, (f32x2){-wi_[t], wi_[t]}, (f32x2){0.f, 0.f});
;             float sr = s2.x, si = s2.y;
;             sr += __shfl_xor(sr, 16); si += __shfl_xor(si, 16); sr += __shfl_xor(sr, 32); si += __shfl_xor(si, 32);
;             if (fq == 0) { e[16 * t + fr] = Rr[t]; e[64 + 16 * t + fr] = Ri[t]; }
;             const float nr = fmaf(a64r[t], Rr[t], fmaf(-a64i[t], Ri[t], sr)), ni = fmaf(a64r[t], Ri[t], fmaf(a64i[t], Rr[t], si)); Rr[t] = nr; Ri[t] = ni;
;         }
;     }
.LBB0_674:
	global_store_dword v[116:117], v240, off offset:-256
	global_store_dword v[116:117], v241, off
	s_waitcnt vmcnt(9)
	v_mfma_f32_16x16x32_bf16 v[136:139], v[108:111], v[26:29], 0
	v_mfma_f32_16x16x32_bf16 v[140:143], v[108:111], v[34:37], 0
	v_mfma_f32_16x16x32_bf16 v[196:199], v[108:111], v[48:51], 0
	v_mfma_f32_16x16x32_bf16 v[200:203], v[108:111], v[56:59], 0
	v_mfma_f32_16x16x32_bf16 v[208:211], v[108:111], v[70:73], 0
	v_mfma_f32_16x16x32_bf16 v[212:215], v[108:111], v[78:81], 0
	v_mfma_f32_16x16x32_bf16 v[224:227], v[108:111], v[88:91], 0
	v_mfma_f32_16x16x32_bf16 v[184:187], v[108:111], v[100:103], 0
	v_mfma_f32_16x16x32_bf16 v[136:139], v[112:115], v[30:33], v[136:139]
	v_mfma_f32_16x16x32_bf16 v[140:143], v[112:115], v[38:41], v[140:143]
	v_mfma_f32_16x16x32_bf16 v[196:199], v[112:115], v[52:55], v[196:199]
	v_mfma_f32_16x16x32_bf16 v[200:203], v[112:115], v[60:63], v[200:203]
	v_mfma_f32_16x16x32_bf16 v[208:211], v[112:115], v[74:77], v[208:211]
	v_mfma_f32_16x16x32_bf16 v[212:215], v[112:115], v[82:85], v[212:215]
	v_mfma_f32_16x16x32_bf16 v[224:227], v[112:115], v[96:99], v[224:227]
	v_mfma_f32_16x16x32_bf16 v[184:187], v[112:115], v[104:107], v[184:187]
	s_nop 6
	v_mov_b32_e32 v144, v136
	v_mov_b32_e32 v204, v196
	v_mov_b32_e32 v216, v208
	v_mov_b32_e32 v228, v224
	v_mov_b32_e32 v145, v140
	v_mov_b32_e32 v205, v200
	v_mov_b32_e32 v217, v212
	v_mov_b32_e32 v229, v184
	v_mov_b32_e32 v146, v137
	v_mov_b32_e32 v206, v197
	v_mov_b32_e32 v218, v209
	v_mov_b32_e32 v188, v225
	v_mov_b32_e32 v147, v141
	v_mov_b32_e32 v207, v201
	v_mov_b32_e32 v219, v213
	v_mov_b32_e32 v189, v185
	v_pk_fma_f32 v[144:145], v[18:19], v[144:145], v[146:147]
	v_pk_fma_f32 v[204:205], v[42:43], v[204:205], v[206:207]
	v_pk_fma_f32 v[216:217], v[64:65], v[216:217], v[218:219]
	v_pk_fma_f32 v[188:189], v[86:87], v[228:229], v[188:189]
	v_mov_b32_e32 v141, v136
	v_mov_b32_e32 v201, v196
	v_mov_b32_e32 v213, v208
	v_mov_b32_e32 v185, v224
	v_pk_fma_f32 v[136:137], v[0:1], v[140:141], v[144:145]
	v_pk_fma_f32 v[196:197], v[4:5], v[200:201], v[204:205]
	v_pk_fma_f32 v[208:209], v[8:9], v[212:213], v[216:217]
	v_pk_fma_f32 v[184:185], v[12:13], v[184:185], v[188:189]
	v_mov_b32_e32 v140, v138
	v_mov_b32_e32 v200, v198
	v_mov_b32_e32 v212, v210
	v_mov_b32_e32 v188, v226
	v_mov_b32_e32 v141, v142
	v_mov_b32_e32 v201, v202
	v_mov_b32_e32 v213, v214
	v_mov_b32_e32 v189, v186
	v_pk_fma_f32 v[140:141], v[18:19], v[136:137], v[140:141]
	v_pk_fma_f32 v[200:201], v[42:43], v[196:197], v[200:201]
	v_pk_fma_f32 v[212:213], v[64:65], v[208:209], v[212:213]
	v_pk_fma_f32 v[188:189], v[86:87], v[184:185], v[188:189]
	v_mov_b32_e32 v142, v139
	v_mov_b32_e32 v202, v199
	v_mov_b32_e32 v214, v211
	v_mov_b32_e32 v186, v227
	v_pk_fma_f32 v[136:137], v[0:1], v[136:137], v[140:141] op_sel:[0,1,0] op_sel_hi:[1,0,1]
	v_pk_fma_f32 v[196:197], v[4:5], v[196:197], v[200:201] op_sel:[0,1,0] op_sel_hi:[1,0,1]
	v_pk_fma_f32 v[208:209], v[8:9], v[208:209], v[212:213] op_sel:[0,1,0] op_sel_hi:[1,0,1]
	v_pk_fma_f32 v[184:185], v[12:13], v[184:185], v[188:189] op_sel:[0,1,0] op_sel_hi:[1,0,1]
	s_nop 0
	s_nop 0
	s_nop 0
	s_nop 0
	v_pk_fma_f32 v[138:139], v[18:19], v[136:137], v[142:143]
	v_pk_fma_f32 v[198:199], v[42:43], v[196:197], v[202:203]
	v_pk_fma_f32 v[210:211], v[64:65], v[208:209], v[214:215]
	v_pk_fma_f32 v[186:187], v[86:87], v[184:185], v[186:187]
	s_nop 0
	s_nop 0
	s_nop 0
	s_nop 0
	v_pk_fma_f32 v[136:137], v[0:1], v[136:137], v[138:139] op_sel:[0,1,0] op_sel_hi:[1,0,1]
	v_pk_fma_f32 v[196:197], v[4:5], v[196:197], v[198:199] op_sel:[0,1,0] op_sel_hi:[1,0,1]
	v_pk_fma_f32 v[208:209], v[8:9], v[208:209], v[210:211] op_sel:[0,1,0] op_sel_hi:[1,0,1]
	v_pk_fma_f32 v[184:185], v[12:13], v[184:185], v[186:187] op_sel:[0,1,0] op_sel_hi:[1,0,1]
	s_nop 0
	s_nop 0
	s_nop 0
	s_nop 0
	v_pk_fma_f32 v[138:139], v[22:23], v[136:137], 0 op_sel_hi:[1,1,0]
	v_pk_fma_f32 v[198:199], v[44:45], v[196:197], 0 op_sel_hi:[1,1,0]
	v_pk_fma_f32 v[210:211], v[66:67], v[208:209], 0 op_sel_hi:[1,1,0]
	v_pk_fma_f32 v[186:187], v[92:93], v[184:185], 0 op_sel_hi:[1,1,0]
	s_nop 0
	s_nop 0
	s_nop 0
	s_nop 0
	v_pk_fma_f32 v[136:137], v[24:25], v[136:137], v[138:139] op_sel:[0,1,0] op_sel_hi:[1,0,1]
	v_pk_fma_f32 v[196:197], v[46:47], v[196:197], v[198:199] op_sel:[0,1,0] op_sel_hi:[1,0,1]
	v_pk_fma_f32 v[208:209], v[68:69], v[208:209], v[210:211] op_sel:[0,1,0] op_sel_hi:[1,0,1]
	v_pk_fma_f32 v[184:185], v[94:95], v[184:185], v[186:187] op_sel:[0,1,0] op_sel_hi:[1,0,1]
	s_nop 1
	v_permlane32_swap_b32_e32 v136, v208
	v_permlane32_swap_b32_e32 v137, v209
	v_permlane32_swap_b32_e32 v196, v184
	v_permlane32_swap_b32_e32 v197, v185
	v_add_f32_e32 v136, v136, v208
	v_add_f32_e32 v196, v196, v184
	v_add_f32_e32 v137, v137, v209
	v_add_f32_e32 v197, v197, v185
	s_nop 0
	v_permlane16_swap_b32_e32 v136, v196
	v_permlane16_swap_b32_e32 v137, v197
	v_add_f32_e32 v136, v136, v196
	v_add_f32_e32 v137, v137, v197
	v_fma_f32 v244, -v243, v241, v136
	v_fma_f32 v245, v243, v240, v137
	v_fma_f32 v240, v242, v240, v244
	v_fma_f32 v241, v242, v241, v245
	v_lshl_add_u64 v[116:117], v[116:117], 0, s[4:5]
	v_add_u32_e32 v20, 64, v20
	s_and_b64 vcc, exec, s[22:23]
	s_cbranch_vccnz .LBB0_702
	s_mov_b32 s24, s40
	s_waitcnt vmcnt(5)
	v_mov_b32_e32 v108, v118
	v_mov_b32_e32 v109, v119
	s_waitcnt vmcnt(4)
	v_mov_b32_e32 v112, v120
	v_mov_b32_e32 v113, v121
	s_waitcnt vmcnt(3)
	v_mov_b32_e32 v114, v122
	v_mov_b32_e32 v115, v123
	s_waitcnt vmcnt(2)
	v_mov_b32_e32 v110, v124
	v_mov_b32_e32 v111, v125
	s_branch .LBB0_671
